# diff-attn QK: K fragments read through 6-buffer register ring with counted lgkmcnt instead of read-wait-mfma per fragment
# speedup vs baseline: 1.0035x; 1.0035x over previous
; #define SBAR() __builtin_amdgcn_sched_barrier(0)
; template <int KB, bool SK>
; __device__ __forceinline__ void qkt(f32x16& p0, f32x16& p1, const char* K_lds, int r32, int hi, const bf16x8* qr, bool act) {
;     if (SK && !act) return;
;     p0 = f32x16{}; p1 = f32x16{};
;     const char* kb[4];
; #pragma unroll
;     for (int dd = 0; dd < 4; ++dd) kb[dd] = K_lds + KB * SHM_K + KSWZ(r32, (dd * 16 + hi * 8) * 2);
; #pragma unroll
;     for (int d0 = 0; d0 < 8; ++d0) { const char* a = kb[d0 & 3] + (d0 >> 2) * 128;
;         bf16x8 b0 = *reinterpret_cast<const bf16x8*>(a);
;         bf16x8 b1 = *reinterpret_cast<const bf16x8*>(a + 32 * 256);
;         p0 = __builtin_amdgcn_mfma_f32_32x32x16_bf16(b0, qr[d0], p0, 0, 0, 0);
;         p1 = __builtin_amdgcn_mfma_f32_32x32x16_bf16(b1, qr[d0], p1, 0, 0, 0); }
; }
; __device__ __forceinline__ void attn_block3(const BlockRef& cur, char* lds, const int wid) {
;     ...
;     for (int t = 0; t < NT; ++t) {
;         f32x16 p0, p1; float mn, alpha; bf16x8 pa0, pa1, pa2, pa3;
;         const int kb = t * KVBLK;
;         qkt<0, false>(p0, p1, K_lds + (t & 1) * SHM_K, r32, hi, qr, true);
;         SBAR(); if (t + 1 < NT) A3_DMA(t + 1);
.LBB0_449:
	s_and_b32 s95, s93, 1
	s_lshl_b32 s7, s95, 14
	s_add_i32 s7, s7, 0
	s_add_i32 s7, s7, 0x10000
	v_add3_u32 v0, s7, v242, v240
	ds_read_b128 v[2:5], v0
	ds_read_b128 v[10:13], v0 offset:8192
	v_add3_u32 v6, s7, v243, v240
	ds_read_b128 v[176:179], v6
	ds_read_b128 v[180:183], v6 offset:8192
	v_add3_u32 v7, s7, v244, v240
	ds_read_b128 v[184:187], v7
	ds_read_b128 v[188:191], v7 offset:8192
	s_mov_b32 s6, s93
	s_waitcnt lgkmcnt(5)
	v_mfma_f32_32x32x16_bf16 v[160:175], v[2:5], v[192:195], 0
	v_add3_u32 v8, s7, v245, v240
	ds_read_b128 v[2:5], v8
	s_waitcnt lgkmcnt(5)
	v_mfma_f32_32x32x16_bf16 v[144:159], v[10:13], v[192:195], 0
	ds_read_b128 v[10:13], v8 offset:8192
	s_waitcnt lgkmcnt(5)
	v_mfma_f32_32x32x16_bf16 v[160:175], v[176:179], v[196:199], v[160:175]
	ds_read_b128 v[176:179], v0 offset:128
	s_waitcnt lgkmcnt(5)
	v_mfma_f32_32x32x16_bf16 v[144:159], v[180:183], v[196:199], v[144:159]
	ds_read_b128 v[180:183], v0 offset:8320
	s_waitcnt lgkmcnt(5)
	v_mfma_f32_32x32x16_bf16 v[160:175], v[184:187], v[200:203], v[160:175]
	ds_read_b128 v[184:187], v6 offset:128
	s_waitcnt lgkmcnt(5)
	v_mfma_f32_32x32x16_bf16 v[144:159], v[188:191], v[200:203], v[144:159]
	ds_read_b128 v[188:191], v6 offset:8320
	s_waitcnt lgkmcnt(5)
	v_mfma_f32_32x32x16_bf16 v[160:175], v[2:5], v[204:207], v[160:175]
	ds_read_b128 v[2:5], v7 offset:128
	s_waitcnt lgkmcnt(5)
	v_mfma_f32_32x32x16_bf16 v[144:159], v[10:13], v[204:207], v[144:159]
	ds_read_b128 v[10:13], v7 offset:8320
	s_waitcnt lgkmcnt(5)
	v_mfma_f32_32x32x16_bf16 v[160:175], v[176:179], v[208:211], v[160:175]
	ds_read_b128 v[176:179], v8 offset:128
	s_waitcnt lgkmcnt(5)
	v_mfma_f32_32x32x16_bf16 v[144:159], v[180:183], v[208:211], v[144:159]
	ds_read_b128 v[180:183], v8 offset:8320
	s_waitcnt lgkmcnt(5)
	v_mfma_f32_32x32x16_bf16 v[160:175], v[184:187], v[212:215], v[160:175]
	s_waitcnt lgkmcnt(4)
	v_mfma_f32_32x32x16_bf16 v[144:159], v[188:191], v[212:215], v[144:159]
	s_waitcnt lgkmcnt(3)
	v_mfma_f32_32x32x16_bf16 v[160:175], v[2:5], v[216:219], v[160:175]
	s_waitcnt lgkmcnt(2)
	v_mfma_f32_32x32x16_bf16 v[144:159], v[10:13], v[216:219], v[144:159]
	s_waitcnt lgkmcnt(1)
	v_mfma_f32_32x32x16_bf16 v[160:175], v[176:179], v[220:223], v[160:175]
	s_waitcnt lgkmcnt(0)
	v_mfma_f32_32x32x16_bf16 v[144:159], v[180:183], v[220:223], v[144:159]
	s_add_i32 s93, s93, 1
	s_cmp_ge_u32 s6, s87
	s_cbranch_scc1 .LBB0_451
	s_and_b32 s6, s93, 1
	s_lshl_b32 s7, s6, 14
	s_add_i32 s7, s83, s7
	s_lshl_b32 s6, s6, 15
	v_lshl_add_u64 v[2:3], s[68:69], 0, v[228:229]
	s_mov_b32 m0, s7
	s_add_i32 s6, s82, s6
	global_load_lds_dwordx4 v[2:3], off
	v_lshl_add_u64 v[2:3], s[68:69], 0, v[226:227]
	v_lshl_add_u64 v[4:5], v[2:3], 0, s[48:49]
	s_mov_b32 m0, s6
	s_add_i32 s20, s6, 0x4000
	global_load_lds_dwordx4 v[4:5], off
	v_lshl_add_u64 v[4:5], s[68:69], 0, v[224:225]
	v_lshl_add_u64 v[6:7], v[4:5], 0, s[48:49]
	s_mov_b32 m0, s20
	v_lshl_add_u64 v[2:3], v[2:3], 0, s[50:51]
	global_load_lds_dwordx4 v[6:7], off
	v_lshl_add_u64 v[6:7], s[68:69], 0, v[230:231]
	s_add_i32 m0, s7, 0x400
	s_nop 0
	global_load_lds_dwordx4 v[6:7], off
	s_add_i32 m0, s6, 0x400
	s_nop 0
	global_load_lds_dwordx4 v[2:3], off
	v_lshl_add_u64 v[2:3], v[4:5], 0, s[50:51]
	s_add_i32 m0, s6, 0x4400
	s_nop 0
	global_load_lds_dwordx4 v[2:3], off
